# cumsum phase: a block's base = its preceding segment totals, loaded together instead of one dependent load per segment
# speedup vs baseline: 1.0267x; 1.0267x over previous
; __device__ __forceinline__ void cumsum_phase(const KA& A, LAS unsigned char* lds, int G) {
;     ...
;     for (int it = blockIdx.x; it < 128; it += G) { const int b = it >> 5, seg = it & 31;
;         float base = 0.f; for (int s2 = 0; s2 < seg; ++s2) base += bt[(b * 32 + s2) * 16 + h];
.LBB0_56:
	v_lshlrev_b32_e32 v5, 2, v4
	global_load_dword v30, v5, s[4:5]
	global_load_dword v31, v5, s[4:5] offset:64
	global_load_dword v32, v5, s[4:5] offset:128
	global_load_dword v33, v5, s[4:5] offset:192
	global_load_dword v34, v5, s[4:5] offset:256
	global_load_dword v35, v5, s[4:5] offset:320
	global_load_dword v36, v5, s[4:5] offset:384
	global_load_dword v37, v5, s[4:5] offset:448
	global_load_dword v38, v5, s[4:5] offset:512
	global_load_dword v39, v5, s[4:5] offset:576
	global_load_dword v40, v5, s[4:5] offset:640
	global_load_dword v41, v5, s[4:5] offset:704
	global_load_dword v42, v5, s[4:5] offset:768
	global_load_dword v43, v5, s[4:5] offset:832
	global_load_dword v44, v5, s[4:5] offset:896
	global_load_dword v45, v5, s[4:5] offset:960
	global_load_dword v46, v5, s[4:5] offset:1024
	global_load_dword v47, v5, s[4:5] offset:1088
	global_load_dword v48, v5, s[4:5] offset:1152
	global_load_dword v49, v5, s[4:5] offset:1216
	global_load_dword v50, v5, s[4:5] offset:1280
	global_load_dword v51, v5, s[4:5] offset:1344
	global_load_dword v52, v5, s[4:5] offset:1408
	global_load_dword v53, v5, s[4:5] offset:1472
	global_load_dword v54, v5, s[4:5] offset:1536
	global_load_dword v55, v5, s[4:5] offset:1600
	global_load_dword v56, v5, s[4:5] offset:1664
	global_load_dword v57, v5, s[4:5] offset:1728
	global_load_dword v58, v5, s[4:5] offset:1792
	global_load_dword v59, v5, s[4:5] offset:1856
	global_load_dword v60, v5, s[4:5] offset:1920
	s_cmp_gt_u32 s9, 0
	s_cselect_b32 s26, 1.0, 0
	s_waitcnt vmcnt(30)
	v_fmac_f32_e32 v2, s26, v30
	s_cmp_gt_u32 s9, 1
	s_cselect_b32 s26, 1.0, 0
	s_waitcnt vmcnt(29)
	v_fmac_f32_e32 v2, s26, v31
	s_cmp_gt_u32 s9, 2
	s_cselect_b32 s26, 1.0, 0
	s_waitcnt vmcnt(28)
	v_fmac_f32_e32 v2, s26, v32
	s_cmp_gt_u32 s9, 3
	s_cselect_b32 s26, 1.0, 0
	s_waitcnt vmcnt(27)
	v_fmac_f32_e32 v2, s26, v33
	s_cmp_gt_u32 s9, 4
	s_cselect_b32 s26, 1.0, 0
	s_waitcnt vmcnt(26)
	v_fmac_f32_e32 v2, s26, v34
	s_cmp_gt_u32 s9, 5
	s_cselect_b32 s26, 1.0, 0
	s_waitcnt vmcnt(25)
	v_fmac_f32_e32 v2, s26, v35
	s_cmp_gt_u32 s9, 6
	s_cselect_b32 s26, 1.0, 0
	s_waitcnt vmcnt(24)
	v_fmac_f32_e32 v2, s26, v36
	s_cmp_gt_u32 s9, 7
	s_cselect_b32 s26, 1.0, 0
	s_waitcnt vmcnt(23)
	v_fmac_f32_e32 v2, s26, v37
	s_cmp_gt_u32 s9, 8
	s_cselect_b32 s26, 1.0, 0
	s_waitcnt vmcnt(22)
	v_fmac_f32_e32 v2, s26, v38
	s_cmp_gt_u32 s9, 9
	s_cselect_b32 s26, 1.0, 0
	s_waitcnt vmcnt(21)
	v_fmac_f32_e32 v2, s26, v39
	s_cmp_gt_u32 s9, 10
	s_cselect_b32 s26, 1.0, 0
	s_waitcnt vmcnt(20)
	v_fmac_f32_e32 v2, s26, v40
	s_cmp_gt_u32 s9, 11
	s_cselect_b32 s26, 1.0, 0
	s_waitcnt vmcnt(19)
	v_fmac_f32_e32 v2, s26, v41
	s_cmp_gt_u32 s9, 12
	s_cselect_b32 s26, 1.0, 0
	s_waitcnt vmcnt(18)
	v_fmac_f32_e32 v2, s26, v42
	s_cmp_gt_u32 s9, 13
	s_cselect_b32 s26, 1.0, 0
	s_waitcnt vmcnt(17)
	v_fmac_f32_e32 v2, s26, v43
	s_cmp_gt_u32 s9, 14
	s_cselect_b32 s26, 1.0, 0
	s_waitcnt vmcnt(16)
	v_fmac_f32_e32 v2, s26, v44
	s_cmp_gt_u32 s9, 15
	s_cselect_b32 s26, 1.0, 0
	s_waitcnt vmcnt(15)
	v_fmac_f32_e32 v2, s26, v45
	s_cmp_gt_u32 s9, 16
	s_cselect_b32 s26, 1.0, 0
	s_waitcnt vmcnt(14)
	v_fmac_f32_e32 v2, s26, v46
	s_cmp_gt_u32 s9, 17
	s_cselect_b32 s26, 1.0, 0
	s_waitcnt vmcnt(13)
	v_fmac_f32_e32 v2, s26, v47
	s_cmp_gt_u32 s9, 18
	s_cselect_b32 s26, 1.0, 0
	s_waitcnt vmcnt(12)
	v_fmac_f32_e32 v2, s26, v48
	s_cmp_gt_u32 s9, 19
	s_cselect_b32 s26, 1.0, 0
	s_waitcnt vmcnt(11)
	v_fmac_f32_e32 v2, s26, v49
	s_cmp_gt_u32 s9, 20
	s_cselect_b32 s26, 1.0, 0
	s_waitcnt vmcnt(10)
	v_fmac_f32_e32 v2, s26, v50
	s_cmp_gt_u32 s9, 21
	s_cselect_b32 s26, 1.0, 0
	s_waitcnt vmcnt(9)
	v_fmac_f32_e32 v2, s26, v51
	s_cmp_gt_u32 s9, 22
	s_cselect_b32 s26, 1.0, 0
	s_waitcnt vmcnt(8)
	v_fmac_f32_e32 v2, s26, v52
	s_cmp_gt_u32 s9, 23
	s_cselect_b32 s26, 1.0, 0
	s_waitcnt vmcnt(7)
	v_fmac_f32_e32 v2, s26, v53
	s_cmp_gt_u32 s9, 24
	s_cselect_b32 s26, 1.0, 0
	s_waitcnt vmcnt(6)
	v_fmac_f32_e32 v2, s26, v54
	s_cmp_gt_u32 s9, 25
	s_cselect_b32 s26, 1.0, 0
	s_waitcnt vmcnt(5)
	v_fmac_f32_e32 v2, s26, v55
	s_cmp_gt_u32 s9, 26
	s_cselect_b32 s26, 1.0, 0
	s_waitcnt vmcnt(4)
	v_fmac_f32_e32 v2, s26, v56
	s_cmp_gt_u32 s9, 27
	s_cselect_b32 s26, 1.0, 0
	s_waitcnt vmcnt(3)
	v_fmac_f32_e32 v2, s26, v57
	s_cmp_gt_u32 s9, 28
	s_cselect_b32 s26, 1.0, 0
	s_waitcnt vmcnt(2)
	v_fmac_f32_e32 v2, s26, v58
	s_cmp_gt_u32 s9, 29
	s_cselect_b32 s26, 1.0, 0
	s_waitcnt vmcnt(1)
	v_fmac_f32_e32 v2, s26, v59
	s_cmp_gt_u32 s9, 30
	s_cselect_b32 s26, 1.0, 0
	s_waitcnt vmcnt(0)
	v_fmac_f32_e32 v2, s26, v60
	s_branch .LBB0_58
